# nt hint also on the bf16 weight stores of the conversion loops
# speedup vs baseline: 1.0022x; 1.0018x over previous
.LBB0_20:
	v_lshlrev_b32_e32 v24, 2, v20
	v_add3_u32 v36, s49, v24, v22
	s_waitcnt lgkmcnt(0)
	s_barrier
	ds_read2_b32 v[24:25], v36 offset1:65
	ds_read2_b32 v[26:27], v36 offset0:130 offset1:195
	v_add_u32_e32 v40, 0x400, v36
	s_ashr_i32 s50, s41, 31
	ds_read2_b32 v[28:29], v40 offset0:4 offset1:69
	ds_read2_b32 v[30:31], v40 offset0:134 offset1:199
	s_lshr_b32 s50, s50, 28
	s_add_i32 s41, s41, s50
	s_ashr_i32 s41, s41, 4
	s_waitcnt lgkmcnt(3)
	v_cvt_pk_bf16_f32 v24, v24, v25
	s_waitcnt lgkmcnt(2)
	v_cvt_pk_bf16_f32 v25, v26, v27
	s_waitcnt lgkmcnt(1)
	v_cvt_pk_bf16_f32 v26, v28, v29
	v_lshl_add_u32 v28, s41, 6, v20
	s_lshl_b32 s50, s41, 11
	s_waitcnt lgkmcnt(0)
	v_cvt_pk_bf16_f32 v27, v30, v31
	v_ashrrev_i32_e32 v29, 31, v28
	ds_read2_b32 v[34:35], v36 offset0:32 offset1:97
	ds_read2_b32 v[36:37], v36 offset0:162 offset1:227
	ds_read2_b32 v[38:39], v40 offset0:36 offset1:101
	ds_read2_b32 v[40:41], v40 offset0:166 offset1:231
	s_sub_i32 s50, s46, s50
	v_lshlrev_b64 v[30:31], 12, v[28:29]
	v_add_u32_e32 v28, 32, v28
	s_ashr_i32 s51, s50, 31
	v_ashrrev_i32_e32 v29, 31, v28
	v_lshl_add_u64 v[32:33], s[50:51], 1, v[18:19]
	v_lshlrev_b64 v[28:29], 12, v[28:29]
	v_lshl_add_u64 v[30:31], v[32:33], 0, v[30:31]
	v_lshl_add_u64 v[28:29], v[32:33], 0, v[28:29]
	s_xor_b64 s[28:29], s[28:29], -1
	s_add_i32 s46, s46, s47
	s_andn2_b64 vcc, exec, s[30:31]
	s_mov_b32 s41, s48
	global_store_dwordx4 v[30:31], v[24:27], off nt
	s_waitcnt lgkmcnt(3)
	s_nop 0
	v_cvt_pk_bf16_f32 v24, v34, v35
	s_waitcnt lgkmcnt(2)
	v_cvt_pk_bf16_f32 v25, v36, v37
	s_waitcnt lgkmcnt(1)
	v_cvt_pk_bf16_f32 v26, v38, v39
	s_waitcnt lgkmcnt(0)
	v_cvt_pk_bf16_f32 v27, v40, v41
	global_store_dwordx4 v[28:29], v[24:27], off nt
	s_cbranch_vccz .LBB0_23

.LBB0_32:
	v_lshlrev_b32_e32 v25, 2, v21
	v_add3_u32 v25, s57, v25, v23
	s_waitcnt lgkmcnt(0)
	s_barrier
	ds_read2_b32 v[26:27], v25 offset1:65
	ds_read2_b32 v[28:29], v25 offset0:130 offset1:195
	v_add_u32_e32 v42, 0x400, v25
	s_ashr_i32 s58, s52, 31
	ds_read2_b32 v[30:31], v42 offset0:4 offset1:69
	ds_read2_b32 v[32:33], v42 offset0:134 offset1:199
	s_lshr_b32 s58, s58, 30
	s_add_i32 s52, s52, s58
	s_ashr_i32 s52, s52, 2
	s_waitcnt lgkmcnt(3)
	v_cvt_pk_bf16_f32 v26, v26, v27
	s_waitcnt lgkmcnt(2)
	v_cvt_pk_bf16_f32 v27, v28, v29
	s_waitcnt lgkmcnt(1)
	v_cvt_pk_bf16_f32 v28, v30, v31
	v_lshl_add_u32 v30, s52, 6, v21
	s_lshl_b32 s58, s52, 9
	s_waitcnt lgkmcnt(0)
	v_cvt_pk_bf16_f32 v29, v32, v33
	v_ashrrev_i32_e32 v31, 31, v30
	ds_read2_b32 v[36:37], v25 offset0:32 offset1:97
	ds_read2_b32 v[38:39], v25 offset0:162 offset1:227
	ds_read2_b32 v[40:41], v42 offset0:36 offset1:101
	ds_read2_b32 v[42:43], v42 offset0:166 offset1:231
	s_sub_i32 s58, s54, s58
	v_lshlrev_b64 v[32:33], 10, v[30:31]
	v_add_u32_e32 v30, 32, v30
	s_ashr_i32 s59, s58, 31
	v_ashrrev_i32_e32 v31, 31, v30
	v_lshl_add_u64 v[34:35], s[58:59], 1, v[18:19]
	v_lshlrev_b64 v[30:31], 10, v[30:31]
	v_lshl_add_u64 v[32:33], v[34:35], 0, v[32:33]
	v_lshl_add_u64 v[30:31], v[34:35], 0, v[30:31]
	s_xor_b64 s[28:29], s[28:29], -1
	s_add_i32 s54, s54, s55
	s_andn2_b64 vcc, exec, s[30:31]
	s_mov_b32 s52, s56
	global_store_dwordx4 v[32:33], v[26:29], off nt
	s_waitcnt lgkmcnt(3)
	s_nop 0
	v_cvt_pk_bf16_f32 v26, v36, v37
	s_waitcnt lgkmcnt(2)
	v_cvt_pk_bf16_f32 v27, v38, v39
	s_waitcnt lgkmcnt(1)
	v_cvt_pk_bf16_f32 v28, v40, v41
	s_waitcnt lgkmcnt(0)
	v_cvt_pk_bf16_f32 v29, v42, v43
	global_store_dwordx4 v[30:31], v[26:29], off nt
	s_cbranch_vccz .LBB0_29

.LBB0_37:
	v_lshlrev_b32_e32 v24, 2, v20
	v_add3_u32 v36, s44, v24, v22
	s_waitcnt lgkmcnt(0)
	s_barrier
	ds_read2_b32 v[24:25], v36 offset1:65
	ds_read2_b32 v[26:27], v36 offset0:130 offset1:195
	v_add_u32_e32 v40, 0x400, v36
	s_ashr_i32 s45, s35, 31
	ds_read2_b32 v[28:29], v40 offset0:4 offset1:69
	ds_read2_b32 v[30:31], v40 offset0:134 offset1:199
	s_lshr_b32 s45, s45, 28
	s_add_i32 s35, s35, s45
	s_ashr_i32 s35, s35, 4
	s_waitcnt lgkmcnt(3)
	v_cvt_pk_bf16_f32 v24, v24, v25
	s_waitcnt lgkmcnt(2)
	v_cvt_pk_bf16_f32 v25, v26, v27
	s_waitcnt lgkmcnt(1)
	v_cvt_pk_bf16_f32 v26, v28, v29
	v_lshl_add_u32 v28, s35, 6, v20
	s_lshl_b32 s45, s35, 11
	s_waitcnt lgkmcnt(0)
	v_cvt_pk_bf16_f32 v27, v30, v31
	v_ashrrev_i32_e32 v29, 31, v28
	ds_read2_b32 v[34:35], v36 offset0:32 offset1:97
	ds_read2_b32 v[36:37], v36 offset0:162 offset1:227
	ds_read2_b32 v[38:39], v40 offset0:36 offset1:101
	ds_read2_b32 v[40:41], v40 offset0:166 offset1:231
	s_sub_i32 s46, s41, s45
	v_lshlrev_b64 v[30:31], 12, v[28:29]
	v_add_u32_e32 v28, 32, v28
	s_ashr_i32 s47, s46, 31
	v_ashrrev_i32_e32 v29, 31, v28
	v_lshl_add_u64 v[32:33], s[46:47], 1, v[18:19]
	v_lshlrev_b64 v[28:29], 12, v[28:29]
	v_lshl_add_u64 v[30:31], v[32:33], 0, v[30:31]
	v_lshl_add_u64 v[28:29], v[32:33], 0, v[28:29]
	s_xor_b64 s[4:5], s[4:5], -1
	s_add_i32 s41, s41, s42
	s_andn2_b64 vcc, exec, s[6:7]
	s_mov_b32 s35, s43
	global_store_dwordx4 v[30:31], v[24:27], off nt
	s_waitcnt lgkmcnt(3)
	s_nop 0
	v_cvt_pk_bf16_f32 v24, v34, v35
	s_waitcnt lgkmcnt(2)
	v_cvt_pk_bf16_f32 v25, v36, v37
	s_waitcnt lgkmcnt(1)
	v_cvt_pk_bf16_f32 v26, v38, v39
	s_waitcnt lgkmcnt(0)
	v_cvt_pk_bf16_f32 v27, v40, v41
	global_store_dwordx4 v[28:29], v[24:27], off nt
	s_cbranch_vccz .LBB0_40

.LBB0_54:
	v_lshlrev_b32_e32 v27, 2, v23
	v_add3_u32 v27, s36, v27, v25
	s_waitcnt lgkmcnt(0)
	s_barrier
	ds_read2_b32 v[28:29], v27 offset1:65
	ds_read2_b32 v[30:31], v27 offset0:130 offset1:195
	v_add_u32_e32 v42, 0x400, v27
	ds_read2_b32 v[32:33], v42 offset0:4 offset1:69
	ds_read2_b32 v[34:35], v42 offset0:134 offset1:199
	s_waitcnt lgkmcnt(3)
	v_cvt_pk_bf16_f32 v28, v28, v29
	s_waitcnt lgkmcnt(2)
	v_cvt_pk_bf16_f32 v29, v30, v31
	s_waitcnt lgkmcnt(1)
	v_cvt_pk_bf16_f32 v30, v32, v33
	v_add_u32_e32 v32, s33, v23
	s_waitcnt lgkmcnt(0)
	v_cvt_pk_bf16_f32 v31, v34, v35
	v_ashrrev_i32_e32 v33, 31, v32
	ds_read2_b32 v[36:37], v27 offset0:32 offset1:97
	ds_read2_b32 v[38:39], v27 offset0:162 offset1:227
	ds_read2_b32 v[40:41], v42 offset0:36 offset1:101
	ds_read2_b32 v[42:43], v42 offset0:166 offset1:231
	v_lshlrev_b64 v[34:35], 8, v[32:33]
	v_add_u32_e32 v32, 32, v32
	v_ashrrev_i32_e32 v33, 31, v32
	v_lshlrev_b64 v[32:33], 8, v[32:33]
	v_lshl_add_u64 v[34:35], v[18:19], 0, v[34:35]
	v_lshl_add_u64 v[32:33], v[18:19], 0, v[32:33]
	s_xor_b64 s[6:7], s[6:7], -1
	s_andn2_b64 vcc, exec, s[8:9]
	s_add_i32 s33, s33, s35
	global_store_dwordx4 v[34:35], v[28:31], off nt
	s_waitcnt lgkmcnt(3)
	s_nop 0
	v_cvt_pk_bf16_f32 v28, v36, v37
	s_waitcnt lgkmcnt(2)
	v_cvt_pk_bf16_f32 v29, v38, v39
	s_waitcnt lgkmcnt(1)
	v_cvt_pk_bf16_f32 v30, v40, v41
	s_waitcnt lgkmcnt(0)
	v_cvt_pk_bf16_f32 v31, v42, v43
	global_store_dwordx4 v[32:33], v[28:31], off nt
	s_cbranch_vccz .LBB0_51

.LBB0_61:
	v_lshlrev_b32_e32 v27, 2, v23
	v_add3_u32 v27, s36, v27, v25
	s_waitcnt lgkmcnt(0)
	s_barrier
	ds_read2_b32 v[28:29], v27 offset1:65
	ds_read2_b32 v[30:31], v27 offset0:130 offset1:195
	v_add_u32_e32 v42, 0x400, v27
	ds_read2_b32 v[32:33], v42 offset0:4 offset1:69
	ds_read2_b32 v[34:35], v42 offset0:134 offset1:199
	s_waitcnt lgkmcnt(3)
	v_cvt_pk_bf16_f32 v28, v28, v29
	s_waitcnt lgkmcnt(2)
	v_cvt_pk_bf16_f32 v29, v30, v31
	s_waitcnt lgkmcnt(1)
	v_cvt_pk_bf16_f32 v30, v32, v33
	v_add_u32_e32 v32, s4, v23
	s_waitcnt lgkmcnt(0)
	v_cvt_pk_bf16_f32 v31, v34, v35
	v_ashrrev_i32_e32 v33, 31, v32
	ds_read2_b32 v[36:37], v27 offset0:32 offset1:97
	ds_read2_b32 v[38:39], v27 offset0:162 offset1:227
	ds_read2_b32 v[40:41], v42 offset0:36 offset1:101
	ds_read2_b32 v[42:43], v42 offset0:166 offset1:231
	v_lshlrev_b64 v[34:35], 8, v[32:33]
	v_add_u32_e32 v32, 32, v32
	v_ashrrev_i32_e32 v33, 31, v32
	v_lshlrev_b64 v[32:33], 8, v[32:33]
	v_lshl_add_u64 v[34:35], v[18:19], 0, v[34:35]
	v_lshl_add_u64 v[32:33], v[18:19], 0, v[32:33]
	s_xor_b64 s[8:9], s[8:9], -1
	s_andn2_b64 vcc, exec, s[10:11]
	s_add_i32 s4, s4, s35
	global_store_dwordx4 v[34:35], v[28:31], off nt
	s_waitcnt lgkmcnt(3)
	s_nop 0
	v_cvt_pk_bf16_f32 v28, v36, v37
	s_waitcnt lgkmcnt(2)
	v_cvt_pk_bf16_f32 v29, v38, v39
	s_waitcnt lgkmcnt(1)
	v_cvt_pk_bf16_f32 v30, v40, v41
	s_waitcnt lgkmcnt(0)
	v_cvt_pk_bf16_f32 v31, v42, v43
	global_store_dwordx4 v[32:33], v[28:31], off nt
	s_cbranch_vccz .LBB0_58

.LBB0_68:
	v_lshlrev_b32_e32 v27, 2, v23
	v_add3_u32 v27, s34, v27, v25
	s_waitcnt lgkmcnt(0)
	s_barrier
	ds_read2_b32 v[28:29], v27 offset1:65
	ds_read2_b32 v[30:31], v27 offset0:130 offset1:195
	v_add_u32_e32 v42, 0x400, v27
	ds_read2_b32 v[32:33], v42 offset0:4 offset1:69
	ds_read2_b32 v[34:35], v42 offset0:134 offset1:199
	s_waitcnt lgkmcnt(3)
	v_cvt_pk_bf16_f32 v28, v28, v29
	s_waitcnt lgkmcnt(2)
	v_cvt_pk_bf16_f32 v29, v30, v31
	s_waitcnt lgkmcnt(1)
	v_cvt_pk_bf16_f32 v30, v32, v33
	v_add_u32_e32 v32, s4, v23
	s_waitcnt lgkmcnt(0)
	v_cvt_pk_bf16_f32 v31, v34, v35
	v_ashrrev_i32_e32 v33, 31, v32
	ds_read2_b32 v[36:37], v27 offset0:32 offset1:97
	ds_read2_b32 v[38:39], v27 offset0:162 offset1:227
	ds_read2_b32 v[40:41], v42 offset0:36 offset1:101
	ds_read2_b32 v[42:43], v42 offset0:166 offset1:231
	v_lshlrev_b64 v[34:35], 8, v[32:33]
	v_add_u32_e32 v32, 32, v32
	v_ashrrev_i32_e32 v33, 31, v32
	v_lshlrev_b64 v[32:33], 8, v[32:33]
	v_lshl_add_u64 v[34:35], v[18:19], 0, v[34:35]
	v_lshl_add_u64 v[32:33], v[18:19], 0, v[32:33]
	s_xor_b64 s[8:9], s[8:9], -1
	s_andn2_b64 vcc, exec, s[10:11]
	s_add_i32 s4, s4, s33
	global_store_dwordx4 v[34:35], v[28:31], off nt
	s_waitcnt lgkmcnt(3)
	s_nop 0
	v_cvt_pk_bf16_f32 v28, v36, v37
	s_waitcnt lgkmcnt(2)
	v_cvt_pk_bf16_f32 v29, v38, v39
	s_waitcnt lgkmcnt(1)
	v_cvt_pk_bf16_f32 v30, v40, v41
	s_waitcnt lgkmcnt(0)
	v_cvt_pk_bf16_f32 v31, v42, v43
	global_store_dwordx4 v[32:33], v[28:31], off nt
	s_cbranch_vccz .LBB0_65

.Ldg0_b98:
	v_lshlrev_b32_e32 v16, 2, v22
	v_add3_u32 v16, s37, v16, v25
	s_waitcnt lgkmcnt(0)
	s_barrier
	ds_read2_b32 v[28:29], v16 offset1:65
	ds_read2_b32 v[30:31], v16 offset0:130 offset1:195
	v_add_u32_e32 v27, 0x400, v16
	s_ashr_i32 s52, s24, 31
	ds_read2_b32 v[32:33], v27 offset0:4 offset1:69
	ds_read2_b32 v[34:35], v27 offset0:134 offset1:199
	s_lshr_b32 s52, s52, 28
	s_add_i32 s24, s24, s52
	s_ashr_i32 s24, s24, 4
	s_waitcnt lgkmcnt(3)
	v_cvt_pk_bf16_f32 v28, v28, v29
	s_waitcnt lgkmcnt(2)
	v_cvt_pk_bf16_f32 v29, v30, v31
	s_waitcnt lgkmcnt(1)
	v_cvt_pk_bf16_f32 v30, v32, v33
	v_lshl_add_u32 v32, s24, 6, v22
	s_lshl_b32 s52, s24, 11
	s_waitcnt lgkmcnt(0)
	v_cvt_pk_bf16_f32 v31, v34, v35
	v_ashrrev_i32_e32 v33, 31, v32
	ds_read2_b32 v[38:39], v16 offset0:32 offset1:97
	ds_read2_b32 v[40:41], v16 offset0:162 offset1:227
	ds_read2_b32 v[42:43], v27 offset0:36 offset1:101
	ds_read2_b32 v[44:45], v27 offset0:166 offset1:231
	s_sub_i32 s52, s26, s52
	v_lshlrev_b64 v[34:35], 12, v[32:33]
	v_add_u32_e32 v32, 32, v32
	s_ashr_i32 s53, s52, 31
	v_ashrrev_i32_e32 v33, 31, v32
	v_lshl_add_u64 v[36:37], s[52:53], 1, v[18:19]
	v_lshlrev_b64 v[32:33], 12, v[32:33]
	v_lshl_add_u64 v[34:35], v[36:37], 0, v[34:35]
	v_lshl_add_u64 v[32:33], v[36:37], 0, v[32:33]
	s_xor_b64 s[48:49], s[48:49], -1
	s_add_i32 s26, s26, s27
	s_andn2_b64 vcc, exec, s[28:29]
	s_mov_b32 s24, s36
	global_store_dwordx4 v[34:35], v[28:31], off nt
	s_waitcnt lgkmcnt(3)
	s_nop 0
	v_cvt_pk_bf16_f32 v28, v38, v39
	s_waitcnt lgkmcnt(2)
	v_cvt_pk_bf16_f32 v29, v40, v41
	s_waitcnt lgkmcnt(1)
	v_cvt_pk_bf16_f32 v30, v42, v43
	s_waitcnt lgkmcnt(0)
	v_cvt_pk_bf16_f32 v31, v44, v45
	global_store_dwordx4 v[32:33], v[28:31], off nt
	s_cbranch_vccz .Ldc_g0_done

.Ldw1_b120:
	v_lshlrev_b32_e32 v24, 2, v21
	v_add3_u32 v34, s44, v24, v22
	v_add_u32_e32 v38, 0x400, v34
	s_waitcnt lgkmcnt(0)
	s_barrier
	s_mul_hi_i32 s24, s24, 0x2e8ba2e9
	ds_read2_b32 v[24:25], v34 offset1:65
	ds_read2_b32 v[26:27], v34 offset0:130 offset1:195
	ds_read2_b32 v[28:29], v38 offset0:4 offset1:69
	ds_read2_b32 v[30:31], v38 offset0:134 offset1:199
	s_lshr_b32 s45, s24, 31
	s_ashr_i32 s24, s24, 3
	s_add_i32 s24, s24, s45
	s_mul_i32 s45, s24, 0xffffea00
	s_add_i32 s46, s27, s45
	s_ashr_i32 s47, s46, 31
	s_waitcnt lgkmcnt(3)
	v_cvt_pk_bf16_f32 v24, v24, v25
	s_waitcnt lgkmcnt(2)
	v_cvt_pk_bf16_f32 v25, v26, v27
	s_waitcnt lgkmcnt(1)
	v_cvt_pk_bf16_f32 v26, v28, v29
	s_waitcnt lgkmcnt(0)
	v_cvt_pk_bf16_f32 v27, v30, v31
	ds_read2_b32 v[30:31], v34 offset0:32 offset1:97
	ds_read2_b32 v[34:35], v34 offset0:162 offset1:227
	ds_read2_b32 v[36:37], v38 offset0:36 offset1:101
	ds_read2_b32 v[38:39], v38 offset0:166 offset1:231
	v_lshl_add_u64 v[32:33], s[46:47], 1, v[18:19]
	v_lshl_add_u32 v40, s24, 6, v21
	v_mad_i64_i32 v[28:29], s[44:45], v40, s76, v[32:33]
	global_store_dwordx4 v[28:29], v[24:27], off nt
	v_add_u32_e32 v28, 32, v40
	v_mad_i64_i32 v[28:29], s[44:45], v28, s76, v[32:33]
	s_xor_b64 s[42:43], s[42:43], -1
	s_add_i32 s27, s27, s36
	s_andn2_b64 vcc, exec, s[28:29]
	s_mov_b32 s24, s37
	s_waitcnt lgkmcnt(3)
	v_cvt_pk_bf16_f32 v24, v30, v31
	s_waitcnt lgkmcnt(2)
	v_cvt_pk_bf16_f32 v25, v34, v35
	s_waitcnt lgkmcnt(1)
	v_cvt_pk_bf16_f32 v26, v36, v37
	s_waitcnt lgkmcnt(0)
	v_cvt_pk_bf16_f32 v27, v38, v39
	global_store_dwordx4 v[28:29], v[24:27], off nt
	s_cbranch_vccz .Ldc_w1_done

.Ldu0_b115:
	v_lshlrev_b32_e32 v16, 2, v21
	v_add3_u32 v16, s46, v16, v23
	s_waitcnt lgkmcnt(0)
	s_barrier
	ds_read2_b32 v[26:27], v16 offset1:65
	ds_read2_b32 v[28:29], v16 offset0:130 offset1:195
	v_add_u32_e32 v25, 0x400, v16
	s_ashr_i32 s47, s37, 31
	ds_read2_b32 v[30:31], v25 offset0:4 offset1:69
	ds_read2_b32 v[32:33], v25 offset0:134 offset1:199
	s_lshr_b32 s47, s47, 28
	s_add_i32 s37, s37, s47
	s_ashr_i32 s37, s37, 4
	s_waitcnt lgkmcnt(3)
	v_cvt_pk_bf16_f32 v26, v26, v27
	s_waitcnt lgkmcnt(2)
	v_cvt_pk_bf16_f32 v27, v28, v29
	s_waitcnt lgkmcnt(1)
	v_cvt_pk_bf16_f32 v28, v30, v31
	v_lshl_add_u32 v30, s37, 6, v21
	s_lshl_b32 s47, s37, 11
	s_waitcnt lgkmcnt(0)
	v_cvt_pk_bf16_f32 v29, v32, v33
	v_ashrrev_i32_e32 v31, 31, v30
	ds_read2_b32 v[36:37], v16 offset0:32 offset1:97
	ds_read2_b32 v[38:39], v16 offset0:162 offset1:227
	ds_read2_b32 v[40:41], v25 offset0:36 offset1:101
	ds_read2_b32 v[42:43], v25 offset0:166 offset1:231
	s_sub_i32 s48, s43, s47
	v_lshlrev_b64 v[32:33], 12, v[30:31]
	v_add_u32_e32 v30, 32, v30
	s_ashr_i32 s49, s48, 31
	v_ashrrev_i32_e32 v31, 31, v30
	v_lshl_add_u64 v[34:35], s[48:49], 1, v[18:19]
	v_lshlrev_b64 v[30:31], 12, v[30:31]
	v_lshl_add_u64 v[32:33], v[34:35], 0, v[32:33]
	v_lshl_add_u64 v[30:31], v[34:35], 0, v[30:31]
	s_xor_b64 s[40:41], s[40:41], -1
	s_add_i32 s43, s43, s44
	s_andn2_b64 vcc, exec, s[28:29]
	s_mov_b32 s37, s45
	global_store_dwordx4 v[32:33], v[26:29], off nt
	s_waitcnt lgkmcnt(3)
	s_nop 0
	v_cvt_pk_bf16_f32 v26, v36, v37
	s_waitcnt lgkmcnt(2)
	v_cvt_pk_bf16_f32 v27, v38, v39
	s_waitcnt lgkmcnt(1)
	v_cvt_pk_bf16_f32 v28, v40, v41
	s_waitcnt lgkmcnt(0)
	v_cvt_pk_bf16_f32 v29, v42, v43
	global_store_dwordx4 v[30:31], v[26:29], off nt
	s_cbranch_vccz .Ldc_u0_done

.LBB0_93:
	v_lshlrev_b32_e32 v24, 2, v21
	v_add3_u32 v36, s37, v24, v22
	s_waitcnt lgkmcnt(0)
	s_barrier
	ds_read2_b32 v[24:25], v36 offset1:65
	ds_read2_b32 v[26:27], v36 offset0:130 offset1:195
	v_add_u32_e32 v40, 0x400, v36
	s_ashr_i32 s83, s24, 31
	ds_read2_b32 v[28:29], v40 offset0:4 offset1:69
	ds_read2_b32 v[30:31], v40 offset0:134 offset1:199
	s_lshr_b32 s83, s83, 28
	s_add_i32 s24, s24, s83
	s_ashr_i32 s24, s24, 4
	s_waitcnt lgkmcnt(3)
	v_cvt_pk_bf16_f32 v24, v24, v25
	s_waitcnt lgkmcnt(2)
	v_cvt_pk_bf16_f32 v25, v26, v27
	s_waitcnt lgkmcnt(1)
	v_cvt_pk_bf16_f32 v26, v28, v29
	v_lshl_add_u32 v28, s24, 6, v21
	s_lshl_b32 s83, s24, 11
	s_waitcnt lgkmcnt(0)
	v_cvt_pk_bf16_f32 v27, v30, v31
	v_ashrrev_i32_e32 v29, 31, v28
	ds_read2_b32 v[34:35], v36 offset0:32 offset1:97
	ds_read2_b32 v[36:37], v36 offset0:162 offset1:227
	ds_read2_b32 v[38:39], v40 offset0:36 offset1:101
	ds_read2_b32 v[40:41], v40 offset0:166 offset1:231
	s_sub_i32 s84, s26, s83
	v_lshlrev_b64 v[30:31], 12, v[28:29]
	v_add_u32_e32 v28, 32, v28
	s_ashr_i32 s85, s84, 31
	v_ashrrev_i32_e32 v29, 31, v28
	v_lshl_add_u64 v[32:33], s[84:85], 1, v[18:19]
	v_lshlrev_b64 v[28:29], 12, v[28:29]
	v_lshl_add_u64 v[30:31], v[32:33], 0, v[30:31]
	v_lshl_add_u64 v[28:29], v[32:33], 0, v[28:29]
	s_xor_b64 s[52:53], s[52:53], -1
	s_add_i32 s26, s26, s27
	s_andn2_b64 vcc, exec, s[28:29]
	s_mov_b32 s24, s36
	global_store_dwordx4 v[30:31], v[24:27], off nt
	s_waitcnt lgkmcnt(3)
	s_nop 0
	v_cvt_pk_bf16_f32 v24, v34, v35
	s_waitcnt lgkmcnt(2)
	v_cvt_pk_bf16_f32 v25, v36, v37
	s_waitcnt lgkmcnt(1)
	v_cvt_pk_bf16_f32 v26, v38, v39
	s_waitcnt lgkmcnt(0)
	v_cvt_pk_bf16_f32 v27, v40, v41
	global_store_dwordx4 v[28:29], v[24:27], off nt
	s_cbranch_vccz .LBB0_96

.LBB0_105:
	v_lshlrev_b32_e32 v24, 2, v21
	v_add3_u32 v36, s84, v24, v22
	s_waitcnt lgkmcnt(0)
	s_barrier
	ds_read2_b32 v[24:25], v36 offset1:65
	ds_read2_b32 v[26:27], v36 offset0:130 offset1:195
	v_add_u32_e32 v40, 0x400, v36
	s_ashr_i32 s85, s48, 31
	ds_read2_b32 v[28:29], v40 offset0:4 offset1:69
	ds_read2_b32 v[30:31], v40 offset0:134 offset1:199
	s_lshr_b32 s85, s85, 30
	s_add_i32 s48, s48, s85
	s_ashr_i32 s48, s48, 2
	s_waitcnt lgkmcnt(3)
	v_cvt_pk_bf16_f32 v24, v24, v25
	s_waitcnt lgkmcnt(2)
	v_cvt_pk_bf16_f32 v25, v26, v27
	s_waitcnt lgkmcnt(1)
	v_cvt_pk_bf16_f32 v26, v28, v29
	v_lshl_add_u32 v28, s48, 6, v21
	s_lshl_b32 s85, s48, 9
	s_waitcnt lgkmcnt(0)
	v_cvt_pk_bf16_f32 v27, v30, v31
	v_ashrrev_i32_e32 v29, 31, v28
	ds_read2_b32 v[34:35], v36 offset0:32 offset1:97
	ds_read2_b32 v[36:37], v36 offset0:162 offset1:227
	ds_read2_b32 v[38:39], v40 offset0:36 offset1:101
	ds_read2_b32 v[40:41], v40 offset0:166 offset1:231
	s_sub_i32 s86, s52, s85
	v_lshlrev_b64 v[30:31], 10, v[28:29]
	v_add_u32_e32 v28, 32, v28
	s_ashr_i32 s87, s86, 31
	v_ashrrev_i32_e32 v29, 31, v28
	v_lshl_add_u64 v[32:33], s[86:87], 1, v[18:19]
	v_lshlrev_b64 v[28:29], 10, v[28:29]
	v_lshl_add_u64 v[30:31], v[32:33], 0, v[30:31]
	v_lshl_add_u64 v[28:29], v[32:33], 0, v[28:29]
	s_xor_b64 s[42:43], s[42:43], -1
	s_add_i32 s52, s52, s53
	s_andn2_b64 vcc, exec, s[28:29]
	s_mov_b32 s48, s83
	global_store_dwordx4 v[30:31], v[24:27], off nt
	s_waitcnt lgkmcnt(3)
	s_nop 0
	v_cvt_pk_bf16_f32 v24, v34, v35
	s_waitcnt lgkmcnt(2)
	v_cvt_pk_bf16_f32 v25, v36, v37
	s_waitcnt lgkmcnt(1)
	v_cvt_pk_bf16_f32 v26, v38, v39
	s_waitcnt lgkmcnt(0)
	v_cvt_pk_bf16_f32 v27, v40, v41
	global_store_dwordx4 v[28:29], v[24:27], off nt
	s_cbranch_vccz .LBB0_102

.LBB0_110:
	v_lshlrev_b32_e32 v24, 2, v21
	v_add3_u32 v36, s44, v24, v22
	s_waitcnt lgkmcnt(0)
	s_barrier
	ds_read2_b32 v[24:25], v36 offset1:65
	ds_read2_b32 v[26:27], v36 offset0:130 offset1:195
	v_add_u32_e32 v40, 0x400, v36
	s_ashr_i32 s45, s24, 31
	ds_read2_b32 v[28:29], v40 offset0:4 offset1:69
	ds_read2_b32 v[30:31], v40 offset0:134 offset1:199
	s_lshr_b32 s45, s45, 28
	s_add_i32 s24, s24, s45
	s_ashr_i32 s24, s24, 4
	s_waitcnt lgkmcnt(3)
	v_cvt_pk_bf16_f32 v24, v24, v25
	s_waitcnt lgkmcnt(2)
	v_cvt_pk_bf16_f32 v25, v26, v27
	s_waitcnt lgkmcnt(1)
	v_cvt_pk_bf16_f32 v26, v28, v29
	v_lshl_add_u32 v28, s24, 6, v21
	s_lshl_b32 s45, s24, 11
	s_waitcnt lgkmcnt(0)
	v_cvt_pk_bf16_f32 v27, v30, v31
	v_ashrrev_i32_e32 v29, 31, v28
	ds_read2_b32 v[34:35], v36 offset0:32 offset1:97
	ds_read2_b32 v[36:37], v36 offset0:162 offset1:227
	ds_read2_b32 v[38:39], v40 offset0:36 offset1:101
	ds_read2_b32 v[40:41], v40 offset0:166 offset1:231
	s_sub_i32 s48, s27, s45
	v_lshlrev_b64 v[30:31], 12, v[28:29]
	v_add_u32_e32 v28, 32, v28
	s_ashr_i32 s49, s48, 31
	v_ashrrev_i32_e32 v29, 31, v28
	v_lshl_add_u64 v[32:33], s[48:49], 1, v[18:19]
	v_lshlrev_b64 v[28:29], 12, v[28:29]
	v_lshl_add_u64 v[30:31], v[32:33], 0, v[30:31]
	v_lshl_add_u64 v[28:29], v[32:33], 0, v[28:29]
	s_xor_b64 s[42:43], s[42:43], -1
	s_add_i32 s27, s27, s36
	s_andn2_b64 vcc, exec, s[28:29]
	s_mov_b32 s24, s37
	global_store_dwordx4 v[30:31], v[24:27], off nt
	s_waitcnt lgkmcnt(3)
	s_nop 0
	v_cvt_pk_bf16_f32 v24, v34, v35
	s_waitcnt lgkmcnt(2)
	v_cvt_pk_bf16_f32 v25, v36, v37
	s_waitcnt lgkmcnt(1)
	v_cvt_pk_bf16_f32 v26, v38, v39
	s_waitcnt lgkmcnt(0)
	v_cvt_pk_bf16_f32 v27, v40, v41
	global_store_dwordx4 v[28:29], v[24:27], off nt
	s_cbranch_vccz .LBB0_113

.LBB0_127:
	v_lshlrev_b32_e32 v26, 2, v23
	v_add3_u32 v36, s46, v26, v24
	s_waitcnt lgkmcnt(0)
	s_barrier
	ds_read2_b32 v[26:27], v36 offset1:65
	ds_read2_b32 v[28:29], v36 offset0:130 offset1:195
	v_add_u32_e32 v40, 0x400, v36
	ds_read2_b32 v[30:31], v40 offset0:4 offset1:69
	ds_read2_b32 v[32:33], v40 offset0:134 offset1:199
	s_waitcnt lgkmcnt(3)
	v_cvt_pk_bf16_f32 v26, v26, v27
	s_waitcnt lgkmcnt(2)
	v_cvt_pk_bf16_f32 v27, v28, v29
	s_waitcnt lgkmcnt(1)
	v_cvt_pk_bf16_f32 v28, v30, v31
	v_add_u32_e32 v30, s43, v23
	s_waitcnt lgkmcnt(0)
	v_cvt_pk_bf16_f32 v29, v32, v33
	v_ashrrev_i32_e32 v31, 31, v30
	ds_read2_b32 v[34:35], v36 offset0:32 offset1:97
	ds_read2_b32 v[36:37], v36 offset0:162 offset1:227
	ds_read2_b32 v[38:39], v40 offset0:36 offset1:101
	ds_read2_b32 v[40:41], v40 offset0:166 offset1:231
	v_lshlrev_b64 v[32:33], 8, v[30:31]
	v_add_u32_e32 v30, 32, v30
	v_ashrrev_i32_e32 v31, 31, v30
	v_lshlrev_b64 v[30:31], 8, v[30:31]
	v_lshl_add_u64 v[32:33], v[18:19], 0, v[32:33]
	v_lshl_add_u64 v[30:31], v[18:19], 0, v[30:31]
	s_xor_b64 s[40:41], s[40:41], -1
	s_andn2_b64 vcc, exec, s[28:29]
	s_add_i32 s43, s43, s45
	global_store_dwordx4 v[32:33], v[26:29], off nt
	s_waitcnt lgkmcnt(3)
	s_nop 0
	v_cvt_pk_bf16_f32 v26, v34, v35
	s_waitcnt lgkmcnt(2)
	v_cvt_pk_bf16_f32 v27, v36, v37
	s_waitcnt lgkmcnt(1)
	v_cvt_pk_bf16_f32 v28, v38, v39
	s_waitcnt lgkmcnt(0)
	v_cvt_pk_bf16_f32 v29, v40, v41
	global_store_dwordx4 v[30:31], v[26:29], off nt
	s_cbranch_vccz .LBB0_124

.LBB0_134:
	v_lshlrev_b32_e32 v26, 2, v23
	v_add3_u32 v36, s44, v26, v24
	s_waitcnt lgkmcnt(0)
	s_barrier
	ds_read2_b32 v[26:27], v36 offset1:65
	ds_read2_b32 v[28:29], v36 offset0:130 offset1:195
	v_add_u32_e32 v40, 0x400, v36
	ds_read2_b32 v[30:31], v40 offset0:4 offset1:69
	ds_read2_b32 v[32:33], v40 offset0:134 offset1:199
	s_waitcnt lgkmcnt(3)
	v_cvt_pk_bf16_f32 v26, v26, v27
	s_waitcnt lgkmcnt(2)
	v_cvt_pk_bf16_f32 v27, v28, v29
	s_waitcnt lgkmcnt(1)
	v_cvt_pk_bf16_f32 v28, v30, v31
	v_add_u32_e32 v30, s24, v23
	s_waitcnt lgkmcnt(0)
	v_cvt_pk_bf16_f32 v29, v32, v33
	v_ashrrev_i32_e32 v31, 31, v30
	ds_read2_b32 v[34:35], v36 offset0:32 offset1:97
	ds_read2_b32 v[36:37], v36 offset0:162 offset1:227
	ds_read2_b32 v[38:39], v40 offset0:36 offset1:101
	ds_read2_b32 v[40:41], v40 offset0:166 offset1:231
	v_lshlrev_b64 v[32:33], 8, v[30:31]
	v_add_u32_e32 v30, 32, v30
	v_ashrrev_i32_e32 v31, 31, v30
	v_lshlrev_b64 v[30:31], 8, v[30:31]
	v_lshl_add_u64 v[32:33], v[18:19], 0, v[32:33]
	v_lshl_add_u64 v[30:31], v[18:19], 0, v[30:31]
	s_xor_b64 s[38:39], s[38:39], -1
	s_andn2_b64 vcc, exec, s[28:29]
	s_add_i32 s24, s24, s43
	global_store_dwordx4 v[32:33], v[26:29], off nt
	s_waitcnt lgkmcnt(3)
	s_nop 0
	v_cvt_pk_bf16_f32 v26, v34, v35
	s_waitcnt lgkmcnt(2)
	v_cvt_pk_bf16_f32 v27, v36, v37
	s_waitcnt lgkmcnt(1)
	v_cvt_pk_bf16_f32 v28, v38, v39
	s_waitcnt lgkmcnt(0)
	v_cvt_pk_bf16_f32 v29, v40, v41
	global_store_dwordx4 v[30:31], v[26:29], off nt
	s_cbranch_vccz .LBB0_131

.LBB0_141:
	v_lshlrev_b32_e32 v26, 2, v23
	v_add3_u32 v36, s42, v26, v24
	s_waitcnt lgkmcnt(0)
	s_barrier
	ds_read2_b32 v[26:27], v36 offset1:65
	ds_read2_b32 v[28:29], v36 offset0:130 offset1:195
	v_add_u32_e32 v40, 0x400, v36
	ds_read2_b32 v[30:31], v40 offset0:4 offset1:69
	ds_read2_b32 v[32:33], v40 offset0:134 offset1:199
	s_waitcnt lgkmcnt(3)
	v_cvt_pk_bf16_f32 v26, v26, v27
	s_waitcnt lgkmcnt(2)
	v_cvt_pk_bf16_f32 v27, v28, v29
	s_waitcnt lgkmcnt(1)
	v_cvt_pk_bf16_f32 v28, v30, v31
	v_add_u32_e32 v30, s24, v23
	s_waitcnt lgkmcnt(0)
	v_cvt_pk_bf16_f32 v29, v32, v33
	v_ashrrev_i32_e32 v31, 31, v30
	ds_read2_b32 v[34:35], v36 offset0:32 offset1:97
	ds_read2_b32 v[36:37], v36 offset0:162 offset1:227
	ds_read2_b32 v[38:39], v40 offset0:36 offset1:101
	ds_read2_b32 v[40:41], v40 offset0:166 offset1:231
	v_lshlrev_b64 v[32:33], 8, v[30:31]
	v_add_u32_e32 v30, 32, v30
	v_ashrrev_i32_e32 v31, 31, v30
	v_lshlrev_b64 v[30:31], 8, v[30:31]
	v_lshl_add_u64 v[32:33], v[18:19], 0, v[32:33]
	v_lshl_add_u64 v[30:31], v[18:19], 0, v[30:31]
	s_xor_b64 s[22:23], s[22:23], -1
	s_andn2_b64 vcc, exec, s[28:29]
	s_add_i32 s24, s24, s41
	global_store_dwordx4 v[32:33], v[26:29], off nt
	s_waitcnt lgkmcnt(3)
	s_nop 0
	v_cvt_pk_bf16_f32 v26, v34, v35
	s_waitcnt lgkmcnt(2)
	v_cvt_pk_bf16_f32 v27, v36, v37
	s_waitcnt lgkmcnt(1)
	v_cvt_pk_bf16_f32 v28, v38, v39
	s_waitcnt lgkmcnt(0)
	v_cvt_pk_bf16_f32 v29, v40, v41
	global_store_dwordx4 v[30:31], v[26:29], off nt
	s_cbranch_vccz .LBB0_138
